# attention: static s_setprio 1 for the lag half removed (both halves at priority 0) on top of v50
# speedup vs baseline: 1.0182x; 1.0111x over previous
.LBB0_356:
	s_or_b64 exec, exec, s[0:1]
	s_sub_i32 s0, 4, s15
	v_cvt_f32_u32_e32 v16, s0
	s_add_i32 s0, 0, 0x21040
	s_waitcnt lgkmcnt(0)
	s_barrier
	v_mul_f32_e32 v16, -2.0, v16
	v_exp_f32_e32 v16, v16
	s_nop 0
	v_mul_f32_e32 v157, 0x3fb8aa3b, v16
	v_mov_b32_e32 v16, s0
	ds_read_b128 v[16:19], v16
	v_readlane_b32 s0, v253, 45
	s_waitcnt lgkmcnt(0)
	v_max_f32_e32 v16, v16, v16
	v_max_f32_e32 v16, 0, v16
	v_max3_f32 v16, v16, v17, v18
	v_mov_b32_e32 v17, s0
	ds_read_b128 v[20:23], v17
	s_waitcnt lgkmcnt(0)
	v_max3_f32 v16, v16, v19, v20
	v_max3_f32 v16, v16, v21, v22
	v_max3_f32 v16, v16, v23, 0
	v_add_f32_e32 v16, 0x42480000, v16
	v_div_scale_f32 v17, s[0:1], v157, v157, v16
	v_rcp_f32_e32 v18, v17
	s_nop 0
	v_fma_f32 v19, -v17, v18, 1.0
	v_fmac_f32_e32 v18, v19, v18
	v_div_scale_f32 v19, vcc, v16, v157, v16
	v_mul_f32_e32 v20, v19, v18
	v_fma_f32 v21, -v17, v20, v19
	v_fmac_f32_e32 v20, v21, v18
	v_fma_f32 v17, -v17, v20, v19
	v_div_fmas_f32 v17, v17, v18, v20
	v_div_fixup_f32 v16, v17, v157, v16
	v_min_f32_e32 v16, 0x46000000, v16
	v_cvt_i32_f32_e32 v16, v16
	v_sub_u32_e32 v17, s14, v16
	v_subrev_u32_e32 v18, s14, v16
	v_add_u32_e32 v16, s14, v16
	v_add_u32_e32 v16, 0x7f, v16
	v_ashrrev_i32_e32 v16, 6, v16
	v_ashrrev_i32_e32 v17, 6, v17
	v_cmp_gt_i32_e32 vcc, 1, v18
	v_min_i32_e32 v16, 63, v16
	s_nop 0
	v_cndmask_b32_e32 v17, 0, v17, vcc
	v_readfirstlane_b32 s0, v16
	v_cndmask_b32_e64 v16, 0, 1, s[54:55]
	v_readfirstlane_b32 s14, v17
	v_cmp_ne_u32_e64 s[10:11], 1, v16
	s_andn2_b64 vcc, exec, s[54:55]
	s_cbranch_vccnz .LBB0_358
	s_setprio 0
